# PLE e GEMM (K=256): first K-loop pass of a unit uses counted DMA waits vmcnt(22) instead of vmcnt(8) so the previous unit's 16 epilogue stores need not drain first
# baseline (speedup 1.0000x reference)
.LBB0_981:
	ds_read_b128 v[148:151], v145
	ds_read_b128 v[152:155], v145 offset:1024
	ds_read_b128 v[156:159], v145 offset:2048
	ds_read_b128 v[160:163], v145 offset:3072
	ds_read_b128 v[164:167], v146
	ds_read_b128 v[168:171], v146 offset:1024
	ds_read_b128 v[172:175], v146 offset:2048
	ds_read_b128 v[176:179], v146 offset:3072
	s_add_i32 s78, s42, 2
	s_add_u32 s79, s40, 0x80
	s_addc_u32 s43, s41, 0
	s_cmp_eq_u32 s60, s42
	s_cselect_b32 s42, s36, s79
	s_cselect_b32 s43, s37, s43
	s_cselect_b32 s81, s39, s77
	s_cselect_b32 s80, s38, s76
	v_lshl_add_u64 v[214:215], s[40:41], 0, v[136:137]
	s_add_i32 m0, s50, 0xc000
	ds_read_b128 v[180:183], v147
	ds_read_b128 v[184:187], v147 offset:1024
	ds_read_b128 v[188:191], v147 offset:2048
	ds_read_b128 v[194:197], v147 offset:3072
	ds_read_b128 v[198:201], v147 offset:4096
	ds_read_b128 v[202:205], v147 offset:5120
	ds_read_b128 v[206:209], v147 offset:6144
	ds_read_b128 v[210:213], v147 offset:7168
	global_load_lds_dwordx4 v[214:215], off
	v_lshl_add_u64 v[214:215], s[40:41], 0, v[138:139]
	s_add_i32 m0, s50, 0xe000
	s_nop 0
	global_load_lds_dwordx4 v[214:215], off
	s_cmp_eq_u32 s78, 2
	s_cbranch_scc1 .Lew_0_0
	s_waitcnt vmcnt(8)
	s_branch .Lew_0_0_d

.Lew_0_0_d:
	s_waitcnt lgkmcnt(0)
	s_barrier
	s_waitcnt lgkmcnt(0)
	v_mfma_f32_16x16x32_bf16 v[120:123], v[148:151], v[180:183], v[120:123]
	v_mfma_f32_16x16x32_bf16 v[124:127], v[156:159], v[180:183], v[124:127]
	v_mfma_f32_16x16x32_bf16 v[108:111], v[148:151], v[188:191], v[108:111]
	v_mfma_f32_16x16x32_bf16 v[104:107], v[156:159], v[188:191], v[104:107]
	v_mfma_f32_16x16x32_bf16 v[92:95], v[148:151], v[198:201], v[92:95]
	v_mfma_f32_16x16x32_bf16 v[88:91], v[156:159], v[198:201], v[88:91]
	v_mfma_f32_16x16x32_bf16 v[76:79], v[148:151], v[206:209], v[76:79]
	v_mfma_f32_16x16x32_bf16 v[72:75], v[156:159], v[206:209], v[72:75]
	v_mfma_f32_16x16x32_bf16 v[120:123], v[152:155], v[184:187], v[120:123]
	v_mfma_f32_16x16x32_bf16 v[124:127], v[160:163], v[184:187], v[124:127]
	v_mfma_f32_16x16x32_bf16 v[108:111], v[152:155], v[194:197], v[108:111]
	v_mfma_f32_16x16x32_bf16 v[104:107], v[160:163], v[194:197], v[104:107]
	v_mfma_f32_16x16x32_bf16 v[92:95], v[152:155], v[202:205], v[92:95]
	v_mfma_f32_16x16x32_bf16 v[88:91], v[160:163], v[202:205], v[88:91]
	v_mfma_f32_16x16x32_bf16 v[76:79], v[152:155], v[210:213], v[76:79]
	v_mfma_f32_16x16x32_bf16 v[72:75], v[160:163], v[210:213], v[72:75]
	v_mfma_f32_16x16x32_bf16 v[116:119], v[164:167], v[180:183], v[116:119]
	v_mfma_f32_16x16x32_bf16 v[112:115], v[172:175], v[180:183], v[112:115]
	v_mfma_f32_16x16x32_bf16 v[100:103], v[164:167], v[188:191], v[100:103]
	v_mfma_f32_16x16x32_bf16 v[96:99], v[172:175], v[188:191], v[96:99]
	v_mfma_f32_16x16x32_bf16 v[84:87], v[164:167], v[198:201], v[84:87]
	v_mfma_f32_16x16x32_bf16 v[80:83], v[172:175], v[198:201], v[80:83]
	v_mfma_f32_16x16x32_bf16 v[68:71], v[164:167], v[206:209], v[68:71]
	v_mfma_f32_16x16x32_bf16 v[64:67], v[172:175], v[206:209], v[64:67]
	v_mfma_f32_16x16x32_bf16 v[116:119], v[168:171], v[184:187], v[116:119]
	v_mfma_f32_16x16x32_bf16 v[112:115], v[176:179], v[184:187], v[112:115]
	v_mfma_f32_16x16x32_bf16 v[100:103], v[168:171], v[194:197], v[100:103]
	v_mfma_f32_16x16x32_bf16 v[96:99], v[176:179], v[194:197], v[96:99]
	v_mfma_f32_16x16x32_bf16 v[84:87], v[168:171], v[202:205], v[84:87]
	v_mfma_f32_16x16x32_bf16 v[80:83], v[176:179], v[202:205], v[80:83]
	v_mfma_f32_16x16x32_bf16 v[68:71], v[168:171], v[210:213], v[68:71]
	v_mfma_f32_16x16x32_bf16 v[64:67], v[176:179], v[210:213], v[64:67]
	s_barrier
	s_add_i32 s79, s61, s49
	v_lshl_add_u64 v[214:215], s[80:81], 0, v[130:131]
	s_mov_b32 m0, s79
	ds_read_b128 v[180:183], v147 offset:16384
	ds_read_b128 v[184:187], v147 offset:17408
	ds_read_b128 v[188:191], v147 offset:18432
	ds_read_b128 v[194:197], v147 offset:19456
	ds_read_b128 v[198:201], v147 offset:20480
	ds_read_b128 v[202:205], v147 offset:21504
	ds_read_b128 v[206:209], v147 offset:22528
	ds_read_b128 v[210:213], v147 offset:23552
	global_load_lds_dwordx4 v[214:215], off
	s_add_i32 m0, s79, 0x2000
	v_lshl_add_u64 v[216:217], s[80:81], 0, v[134:135]
	s_add_u32 s80, s80, s6
	s_addc_u32 s81, s81, s7
	s_add_i32 s79, s62, s49
	global_load_lds_dwordx4 v[216:217], off
	v_lshl_add_u64 v[218:219], s[80:81], 0, v[130:131]
	s_mov_b32 m0, s79
	v_lshl_add_u64 v[220:221], s[80:81], 0, v[134:135]
	global_load_lds_dwordx4 v[218:219], off
	s_add_i32 m0, s79, 0x2000
	v_lshl_add_u64 v[222:223], s[42:43], 0, v[128:129]
	global_load_lds_dwordx4 v[220:221], off
	s_mov_b32 m0, s50
	v_lshl_add_u64 v[224:225], s[42:43], 0, v[132:133]
	global_load_lds_dwordx4 v[222:223], off
	s_mov_b32 m0, s51
	s_nop 0
	global_load_lds_dwordx4 v[224:225], off
	s_cmp_eq_u32 s78, 2
	s_cbranch_scc1 .Lew_0_1
	s_waitcnt vmcnt(8)
	s_branch .Lew_0_1_d

.Lew_0_1_d:
	s_waitcnt lgkmcnt(0)
	s_barrier
	s_waitcnt lgkmcnt(0)
	v_mfma_f32_16x16x32_bf16 v[60:63], v[148:151], v[180:183], v[60:63]
	v_mfma_f32_16x16x32_bf16 v[56:59], v[156:159], v[180:183], v[56:59]
	v_mfma_f32_16x16x32_bf16 v[44:47], v[148:151], v[188:191], v[44:47]
	v_mfma_f32_16x16x32_bf16 v[40:43], v[156:159], v[188:191], v[40:43]
	v_mfma_f32_16x16x32_bf16 v[28:31], v[148:151], v[198:201], v[28:31]
	v_mfma_f32_16x16x32_bf16 v[24:27], v[156:159], v[198:201], v[24:27]
	v_mfma_f32_16x16x32_bf16 v[12:15], v[148:151], v[206:209], v[12:15]
	v_mfma_f32_16x16x32_bf16 v[8:11], v[156:159], v[206:209], v[8:11]
	v_mfma_f32_16x16x32_bf16 v[60:63], v[152:155], v[184:187], v[60:63]
	v_mfma_f32_16x16x32_bf16 v[56:59], v[160:163], v[184:187], v[56:59]
	v_mfma_f32_16x16x32_bf16 v[44:47], v[152:155], v[194:197], v[44:47]
	v_mfma_f32_16x16x32_bf16 v[40:43], v[160:163], v[194:197], v[40:43]
	v_mfma_f32_16x16x32_bf16 v[28:31], v[152:155], v[202:205], v[28:31]
	v_mfma_f32_16x16x32_bf16 v[24:27], v[160:163], v[202:205], v[24:27]
	v_mfma_f32_16x16x32_bf16 v[12:15], v[152:155], v[210:213], v[12:15]
	v_mfma_f32_16x16x32_bf16 v[8:11], v[160:163], v[210:213], v[8:11]
	v_mfma_f32_16x16x32_bf16 v[52:55], v[164:167], v[180:183], v[52:55]
	v_mfma_f32_16x16x32_bf16 v[48:51], v[172:175], v[180:183], v[48:51]
	v_mfma_f32_16x16x32_bf16 v[36:39], v[164:167], v[188:191], v[36:39]
	v_mfma_f32_16x16x32_bf16 v[32:35], v[172:175], v[188:191], v[32:35]
	v_mfma_f32_16x16x32_bf16 v[20:23], v[164:167], v[198:201], v[20:23]
	v_mfma_f32_16x16x32_bf16 v[16:19], v[172:175], v[198:201], v[16:19]
	v_mfma_f32_16x16x32_bf16 v[4:7], v[164:167], v[206:209], v[4:7]
	v_mfma_f32_16x16x32_bf16 v[0:3], v[172:175], v[206:209], v[0:3]
	v_mfma_f32_16x16x32_bf16 v[52:55], v[168:171], v[184:187], v[52:55]
	v_mfma_f32_16x16x32_bf16 v[48:51], v[176:179], v[184:187], v[48:51]
	v_mfma_f32_16x16x32_bf16 v[36:39], v[168:171], v[194:197], v[36:39]
	v_mfma_f32_16x16x32_bf16 v[32:35], v[176:179], v[194:197], v[32:35]
	v_mfma_f32_16x16x32_bf16 v[20:23], v[168:171], v[202:205], v[20:23]
	v_mfma_f32_16x16x32_bf16 v[16:19], v[176:179], v[202:205], v[16:19]
	v_mfma_f32_16x16x32_bf16 v[4:7], v[168:171], v[210:213], v[4:7]
	v_mfma_f32_16x16x32_bf16 v[0:3], v[176:179], v[210:213], v[0:3]
	s_barrier
	s_add_i32 s79, 0, 0x18000
	s_add_i32 s80, 0, 0x1c000
	v_add_u32_e32 v160, s79, v143
	v_add_u32_e32 v176, s80, v143
	ds_read_b128 v[148:151], v160
	ds_read_b128 v[152:155], v160 offset:1024
	ds_read_b128 v[156:159], v160 offset:2048
	ds_read_b128 v[160:163], v160 offset:3072
	ds_read_b128 v[164:167], v176
	ds_read_b128 v[168:171], v176 offset:1024
	ds_read_b128 v[172:175], v176 offset:2048
	ds_read_b128 v[176:179], v176 offset:3072
	s_add_u32 s42, s42, s6
	s_addc_u32 s43, s43, s7
	s_mov_b32 m0, s52
	v_lshl_add_u64 v[226:227], s[42:43], 0, v[128:129]
	ds_read_b128 v[180:183], v147 offset:32768
	ds_read_b128 v[184:187], v147 offset:33792
	ds_read_b128 v[188:191], v147 offset:34816
	ds_read_b128 v[194:197], v147 offset:35840
	ds_read_b128 v[198:201], v147 offset:36864
	ds_read_b128 v[202:205], v147 offset:37888
	ds_read_b128 v[206:209], v147 offset:38912
	ds_read_b128 v[210:213], v147 offset:39936
	global_load_lds_dwordx4 v[226:227], off
	v_lshl_add_u64 v[226:227], s[42:43], 0, v[132:133]
	s_mov_b32 m0, s53
	s_nop 0
	global_load_lds_dwordx4 v[226:227], off
	s_waitcnt vmcnt(8)
	s_waitcnt lgkmcnt(0)
	s_barrier
	s_waitcnt lgkmcnt(0)
	v_mfma_f32_16x16x32_bf16 v[120:123], v[148:151], v[180:183], v[120:123]
	v_mfma_f32_16x16x32_bf16 v[124:127], v[156:159], v[180:183], v[124:127]
	v_mfma_f32_16x16x32_bf16 v[108:111], v[148:151], v[188:191], v[108:111]
	v_mfma_f32_16x16x32_bf16 v[104:107], v[156:159], v[188:191], v[104:107]
	v_mfma_f32_16x16x32_bf16 v[92:95], v[148:151], v[198:201], v[92:95]
	v_mfma_f32_16x16x32_bf16 v[88:91], v[156:159], v[198:201], v[88:91]
	v_mfma_f32_16x16x32_bf16 v[76:79], v[148:151], v[206:209], v[76:79]
	v_mfma_f32_16x16x32_bf16 v[72:75], v[156:159], v[206:209], v[72:75]
	v_mfma_f32_16x16x32_bf16 v[120:123], v[152:155], v[184:187], v[120:123]
	v_mfma_f32_16x16x32_bf16 v[124:127], v[160:163], v[184:187], v[124:127]
	v_mfma_f32_16x16x32_bf16 v[108:111], v[152:155], v[194:197], v[108:111]
	v_mfma_f32_16x16x32_bf16 v[104:107], v[160:163], v[194:197], v[104:107]
	v_mfma_f32_16x16x32_bf16 v[92:95], v[152:155], v[202:205], v[92:95]
	v_mfma_f32_16x16x32_bf16 v[88:91], v[160:163], v[202:205], v[88:91]
	v_mfma_f32_16x16x32_bf16 v[76:79], v[152:155], v[210:213], v[76:79]
	v_mfma_f32_16x16x32_bf16 v[72:75], v[160:163], v[210:213], v[72:75]
	v_mfma_f32_16x16x32_bf16 v[116:119], v[164:167], v[180:183], v[116:119]
	v_mfma_f32_16x16x32_bf16 v[112:115], v[172:175], v[180:183], v[112:115]
	v_mfma_f32_16x16x32_bf16 v[100:103], v[164:167], v[188:191], v[100:103]
	v_mfma_f32_16x16x32_bf16 v[96:99], v[172:175], v[188:191], v[96:99]
	v_mfma_f32_16x16x32_bf16 v[84:87], v[164:167], v[198:201], v[84:87]
	v_mfma_f32_16x16x32_bf16 v[80:83], v[172:175], v[198:201], v[80:83]
	v_mfma_f32_16x16x32_bf16 v[68:71], v[164:167], v[206:209], v[68:71]
	v_mfma_f32_16x16x32_bf16 v[64:67], v[172:175], v[206:209], v[64:67]
	v_mfma_f32_16x16x32_bf16 v[116:119], v[168:171], v[184:187], v[116:119]
	v_mfma_f32_16x16x32_bf16 v[112:115], v[176:179], v[184:187], v[112:115]
	v_mfma_f32_16x16x32_bf16 v[100:103], v[168:171], v[194:197], v[100:103]
	v_mfma_f32_16x16x32_bf16 v[96:99], v[176:179], v[194:197], v[96:99]
	v_mfma_f32_16x16x32_bf16 v[84:87], v[168:171], v[202:205], v[84:87]
	v_mfma_f32_16x16x32_bf16 v[80:83], v[176:179], v[202:205], v[80:83]
	v_mfma_f32_16x16x32_bf16 v[68:71], v[168:171], v[210:213], v[68:71]
	v_mfma_f32_16x16x32_bf16 v[64:67], v[176:179], v[210:213], v[64:67]
	s_barrier
	s_add_i32 s42, s79, s49
	v_lshl_add_u64 v[214:215], v[214:215], 0, s[18:19]
	s_mov_b32 m0, s42
	ds_read_b128 v[180:183], v147 offset:49152
	ds_read_b128 v[184:187], v147 offset:50176
	ds_read_b128 v[188:191], v147 offset:51200
	ds_read_b128 v[194:197], v147 offset:52224
	ds_read_b128 v[198:201], v147 offset:53248
	ds_read_b128 v[202:205], v147 offset:54272
	ds_read_b128 v[206:209], v147 offset:55296
	ds_read_b128 v[210:213], v147 offset:56320
	global_load_lds_dwordx4 v[214:215], off
	v_lshl_add_u64 v[214:215], v[216:217], 0, s[18:19]
	s_add_i32 m0, s42, 0x2000
	s_add_i32 s42, s80, s49
	global_load_lds_dwordx4 v[214:215], off
	v_lshl_add_u64 v[214:215], v[218:219], 0, s[18:19]
	s_mov_b32 m0, s42
	s_nop 0
	global_load_lds_dwordx4 v[214:215], off
	v_lshl_add_u64 v[214:215], v[220:221], 0, s[18:19]
	s_add_i32 m0, s42, 0x2000
	s_nop 0
	global_load_lds_dwordx4 v[214:215], off
	v_lshl_add_u64 v[214:215], v[222:223], 0, s[18:19]
	s_mov_b32 m0, s55
	s_nop 0
	global_load_lds_dwordx4 v[214:215], off
	v_lshl_add_u64 v[214:215], v[224:225], 0, s[18:19]
	s_mov_b32 m0, s56
	s_nop 0
	global_load_lds_dwordx4 v[214:215], off
	s_waitcnt vmcnt(8)
	s_waitcnt lgkmcnt(0)
	s_barrier
	s_waitcnt lgkmcnt(0)
	v_mfma_f32_16x16x32_bf16 v[60:63], v[148:151], v[180:183], v[60:63]
	v_mfma_f32_16x16x32_bf16 v[56:59], v[156:159], v[180:183], v[56:59]
	v_mfma_f32_16x16x32_bf16 v[44:47], v[148:151], v[188:191], v[44:47]
	v_mfma_f32_16x16x32_bf16 v[40:43], v[156:159], v[188:191], v[40:43]
	v_mfma_f32_16x16x32_bf16 v[28:31], v[148:151], v[198:201], v[28:31]
	v_mfma_f32_16x16x32_bf16 v[24:27], v[156:159], v[198:201], v[24:27]
	v_mfma_f32_16x16x32_bf16 v[12:15], v[148:151], v[206:209], v[12:15]
	v_mfma_f32_16x16x32_bf16 v[8:11], v[156:159], v[206:209], v[8:11]
	v_mfma_f32_16x16x32_bf16 v[60:63], v[152:155], v[184:187], v[60:63]
	v_mfma_f32_16x16x32_bf16 v[56:59], v[160:163], v[184:187], v[56:59]
	v_mfma_f32_16x16x32_bf16 v[44:47], v[152:155], v[194:197], v[44:47]
	v_mfma_f32_16x16x32_bf16 v[40:43], v[160:163], v[194:197], v[40:43]
	v_mfma_f32_16x16x32_bf16 v[28:31], v[152:155], v[202:205], v[28:31]
	v_mfma_f32_16x16x32_bf16 v[24:27], v[160:163], v[202:205], v[24:27]
	v_mfma_f32_16x16x32_bf16 v[12:15], v[152:155], v[210:213], v[12:15]
	v_mfma_f32_16x16x32_bf16 v[8:11], v[160:163], v[210:213], v[8:11]
	v_mfma_f32_16x16x32_bf16 v[52:55], v[164:167], v[180:183], v[52:55]
	v_mfma_f32_16x16x32_bf16 v[48:51], v[172:175], v[180:183], v[48:51]
	v_mfma_f32_16x16x32_bf16 v[36:39], v[164:167], v[188:191], v[36:39]
	v_mfma_f32_16x16x32_bf16 v[32:35], v[172:175], v[188:191], v[32:35]
	v_mfma_f32_16x16x32_bf16 v[20:23], v[164:167], v[198:201], v[20:23]
	v_mfma_f32_16x16x32_bf16 v[16:19], v[172:175], v[198:201], v[16:19]
	v_mfma_f32_16x16x32_bf16 v[4:7], v[164:167], v[206:209], v[4:7]
	v_mfma_f32_16x16x32_bf16 v[0:3], v[172:175], v[206:209], v[0:3]
	v_mfma_f32_16x16x32_bf16 v[52:55], v[168:171], v[184:187], v[52:55]
	v_mfma_f32_16x16x32_bf16 v[48:51], v[176:179], v[184:187], v[48:51]
	v_mfma_f32_16x16x32_bf16 v[36:39], v[168:171], v[194:197], v[36:39]
	v_mfma_f32_16x16x32_bf16 v[32:35], v[176:179], v[194:197], v[32:35]
	v_mfma_f32_16x16x32_bf16 v[20:23], v[168:171], v[202:205], v[20:23]
	v_mfma_f32_16x16x32_bf16 v[16:19], v[176:179], v[202:205], v[16:19]
	v_mfma_f32_16x16x32_bf16 v[4:7], v[168:171], v[210:213], v[4:7]
	v_mfma_f32_16x16x32_bf16 v[0:3], v[176:179], v[210:213], v[0:3]
	s_barrier
	s_add_u32 s40, s40, 0x100
	s_addc_u32 s41, s41, 0
	s_add_u32 s76, s76, 0x100
	s_addc_u32 s77, s77, 0
	s_cmp_ge_i32 s78, s59
	s_mov_b32 s42, s78
	s_cbranch_scc0 .LBB0_981
